# pass A: next unit's 10 input loads prefetched one unit ahead (software pipelining across units)
# speedup vs baseline: 1.0245x; 1.0003x over previous
.LBB0_199:
	s_bitcmp0_b32 s64, 0
	s_cselect_b64 s[94:95], -1, 0
	s_cmp_lt_i32 s20, 1
	s_cselect_b64 s[2:3], -1, 0
	s_or_b64 s[2:3], s[94:95], s[2:3]
	s_mov_b32 s1, 0
	s_and_b64 vcc, exec, s[2:3]
	s_cbranch_vccnz .LBB0_222
	s_cmp_lt_i32 s64, 64
	s_cselect_b32 s0, 64, 0xffffffc0
	s_add_i32 s8, s64, s0
	s_addk_i32 s8, 0x700
	s_add_u32 s34, s90, 0x1e800000
	s_addc_u32 s35, s91, 0
	v_readlane_b32 s2, v246, 36
	s_add_u32 s56, s90, 0x1ea00000
	v_readlane_b32 s3, v246, 37
	s_addc_u32 s57, s91, 0
	s_movk_i32 s9, 0x2880
	v_mov_b64_e32 v[32:33], s[2:3]
	s_movk_i32 s10, 0x1000
	s_mov_b32 s11, 0x800000
	s_mov_b32 s16, 0x3f317217
	s_mov_b32 s17, 0x7f800000
	v_mov_b32_e32 v46, 0x41b17218
	s_movk_i32 s18, 0x7f
	s_movk_i32 s19, 0x2040
	s_add_i32 s21, 0, 0x8100
	s_movk_i32 s22, 0x480
	s_movk_i32 s23, 0x48
	v_mov_b32_e32 v35, 0
	s_movk_i32 s24, 0x90
	s_mov_b32 s25, 0
	s_mov_b32 s99, s64
	s_lshl_b32 s100, s99, 3
	s_lshl_b32 s101, s99, 6
	s_and_b32 s100, s100, 0xffffe000
	s_and_b32 s101, s101, 0x1fc0
	s_or_b32 s100, s100, s101
	s_and_b32 s98, s99, 0x380
	v_ashrrev_i32_e32 v206, 6, v210
	v_bfi_b32 v208, -4, v206, v210
	v_lshlrev_b32_e32 v208, 4, v208
	v_mov_b32_e32 v209, 0
	v_bfe_u32 v206, v210, 2, 6
	v_or_b32_e32 v206, s100, v206
	v_mad_i64_i32 v[200:201], vcc, v206, s9, v[32:33]
	s_lshl_b32 s100, s98, 1
	s_mov_b32 s101, 0
	v_lshl_add_u64 v[200:201], v[200:201], 0, s[100:101]
	v_lshl_add_u64 v[200:201], v[208:209], 1, v[200:201]
	v_add_u32_e32 v202, s98, v208
	v_mov_b32_e32 v203, 0
	v_lshl_add_u64 v[202:203], v[202:203], 2, s[54:55]
	s_movk_i32 s100, 0x1000
	v_lshl_add_u64 v[204:205], v[200:201], 0, s[100:101]
	global_load_dwordx4 v[160:163], v[200:201], off offset:2048
	global_load_dwordx4 v[164:167], v[200:201], off offset:2064
	global_load_dwordx4 v[168:171], v[202:203], off
	global_load_dwordx4 v[172:175], v[202:203], off offset:16
	global_load_dwordx4 v[176:179], v[200:201], off offset:16
	global_load_dwordx4 v[180:183], v[200:201], off
	global_load_dwordx4 v[184:187], v[204:205], off
	global_load_dwordx4 v[188:191], v[204:205], off offset:16
	global_load_dwordx4 v[192:195], v[202:203], off offset:48
	global_load_dwordx4 v[196:199], v[202:203], off offset:32
	s_branch .LBB0_202

.LBB0_208:
	s_lshl_b32 s0, s58, 3
	s_lshl_b32 s2, s58, 6
	v_mov_b32_e32 v36, v210
	s_and_b32 s0, s0, 0xffffe000
	s_and_b32 s2, s2, 0x1fc0
	s_or_b32 s27, s0, s2
	v_ashrrev_i32_e32 v0, 6, v36
	v_bfe_u32 v37, v36, 2, 6
	s_and_b32 s4, s58, 0x380
	v_bfi_b32 v34, -4, v0, v36
	v_or_b32_e32 v0, s27, v37
	v_lshlrev_b32_e32 v24, 4, v34
	v_mad_i64_i32 v[0:1], s[2:3], v0, s9, v[32:33]
	s_lshl_b32 s0, s4, 1
	v_lshl_add_u64 v[0:1], v[0:1], 0, s[0:1]
	v_ashrrev_i32_e32 v25, 31, v24
	v_lshl_add_u64 v[0:1], v[24:25], 1, v[0:1]
	s_waitcnt vmcnt(0)
	v_mov_b32_e32 v26, v160
	v_mov_b32_e32 v27, v161
	v_mov_b32_e32 v28, v162
	v_mov_b32_e32 v29, v163
	v_mov_b32_e32 v38, v164
	v_mov_b32_e32 v39, v165
	v_mov_b32_e32 v40, v166
	v_mov_b32_e32 v41, v167
	v_add_u32_e32 v2, s4, v24
	v_ashrrev_i32_e32 v3, 31, v2
	v_lshl_add_u64 v[20:21], v[2:3], 2, s[54:55]
	v_mov_b32_e32 v42, v168
	v_mov_b32_e32 v43, v169
	v_mov_b32_e32 v44, v170
	v_mov_b32_e32 v45, v171
	v_mov_b32_e32 v48, v172
	v_mov_b32_e32 v49, v173
	v_mov_b32_e32 v50, v174
	v_mov_b32_e32 v51, v175
	v_mul_u32_u24_e32 v2, 0x204, v37
	v_lshlrev_b32_e32 v3, 6, v34
	v_add3_u32 v47, 0, v2, v3
	v_add_co_u32_e32 v2, vcc, s10, v0
	v_readfirstlane_b32 s26, v36
	s_nop 0
	v_addc_co_u32_e32 v3, vcc, 0, v1, vcc
	v_mov_b32_e32 v4, v176
	v_mov_b32_e32 v5, v177
	v_mov_b32_e32 v6, v178
	v_mov_b32_e32 v7, v179
	v_mov_b32_e32 v12, v180
	v_mov_b32_e32 v13, v181
	v_mov_b32_e32 v14, v182
	v_mov_b32_e32 v15, v183
	v_mov_b32_e32 v8, v184
	v_mov_b32_e32 v9, v185
	v_mov_b32_e32 v10, v186
	v_mov_b32_e32 v11, v187
	s_nop 0
	v_mov_b32_e32 v0, v188
	v_mov_b32_e32 v1, v189
	v_mov_b32_e32 v2, v190
	v_mov_b32_e32 v3, v191
	s_nop 0
	v_mov_b32_e32 v16, v192
	v_mov_b32_e32 v17, v193
	v_mov_b32_e32 v18, v194
	v_mov_b32_e32 v19, v195
	s_nop 0
	v_mov_b32_e32 v20, v196
	v_mov_b32_e32 v21, v197
	v_mov_b32_e32 v22, v198
	v_mov_b32_e32 v23, v199
	s_add_i32 s98, s25, 1
	s_cmp_ge_u32 s98, s20
	s_cbranch_scc1 .Lpa1_nopf
	s_lshl_b32 s99, s98, 8
	s_add_i32 s99, s99, s64
	s_cmp_gt_u32 s98, 7
	s_cselect_b32 s99, s8, s99
	s_lshl_b32 s100, s99, 3
	s_lshl_b32 s101, s99, 6
	s_and_b32 s100, s100, 0xffffe000
	s_and_b32 s101, s101, 0x1fc0
	s_or_b32 s100, s100, s101
	s_and_b32 s98, s99, 0x380
	v_ashrrev_i32_e32 v206, 6, v210
	v_bfi_b32 v208, -4, v206, v210
	v_lshlrev_b32_e32 v208, 4, v208
	v_mov_b32_e32 v209, 0
	v_bfe_u32 v206, v210, 2, 6
	v_or_b32_e32 v206, s100, v206
	v_mad_i64_i32 v[200:201], vcc, v206, s9, v[32:33]
	s_lshl_b32 s100, s98, 1
	s_mov_b32 s101, 0
	v_lshl_add_u64 v[200:201], v[200:201], 0, s[100:101]
	v_lshl_add_u64 v[200:201], v[208:209], 1, v[200:201]
	v_add_u32_e32 v202, s98, v208
	v_mov_b32_e32 v203, 0
	v_lshl_add_u64 v[202:203], v[202:203], 2, s[54:55]
	s_movk_i32 s100, 0x1000
	v_lshl_add_u64 v[204:205], v[200:201], 0, s[100:101]
	global_load_dwordx4 v[160:163], v[200:201], off offset:2048
	global_load_dwordx4 v[164:167], v[200:201], off offset:2064
	global_load_dwordx4 v[168:171], v[202:203], off
	global_load_dwordx4 v[172:175], v[202:203], off offset:16
	global_load_dwordx4 v[176:179], v[200:201], off offset:16
	global_load_dwordx4 v[180:183], v[200:201], off
	global_load_dwordx4 v[184:187], v[204:205], off
	global_load_dwordx4 v[188:191], v[204:205], off offset:16
	global_load_dwordx4 v[192:195], v[202:203], off offset:48
	global_load_dwordx4 v[196:199], v[202:203], off offset:32
.Lpa1_nopf:
	s_nop 0
	v_lshlrev_b32_e32 v25, 16, v26
	v_and_b32_e32 v26, 0xffff0000, v26
	v_lshlrev_b32_e32 v30, 16, v27
	v_and_b32_e32 v27, 0xffff0000, v27
	v_mul_f32_e32 v25, 0xbfb8aa3b, v25
	v_mul_f32_e32 v26, 0xbfb8aa3b, v26
	v_mul_f32_e32 v27, 0xbfb8aa3b, v27
	v_exp_f32_e32 v25, v25
	v_exp_f32_e32 v26, v26
	v_exp_f32_e32 v27, v27
	v_lshlrev_b32_e32 v52, 16, v28
	v_and_b32_e32 v53, 0xffff0000, v28
	v_mul_f32_e32 v28, 0xbfb8aa3b, v30
	v_exp_f32_e32 v28, v28
	v_lshlrev_b32_e32 v54, 16, v29
	v_and_b32_e32 v55, 0xffff0000, v29
	v_add_f32_e32 v25, 1.0, v25
	v_add_f32_e32 v29, 1.0, v26
	v_add_f32_e32 v30, 1.0, v27
	v_rcp_f32_e32 v26, v25
	v_rcp_f32_e32 v27, v29
	v_add_f32_e32 v28, 1.0, v28
	v_rcp_f32_e32 v28, v28
	v_rcp_f32_e32 v29, v30
	s_nop 0
	v_pk_add_f32 v[30:31], v[42:43], 1.0 op_sel_hi:[1,0] neg_lo:[1,0] neg_hi:[1,0]
	v_lshlrev_b32_e32 v56, 16, v38
	v_pk_fma_f32 v[26:27], v[30:31], v[26:27], v[42:43]
	v_and_b32_e32 v57, 0xffff0000, v38
	v_cmp_gt_f32_e32 vcc, s11, v26
	v_lshlrev_b32_e32 v58, 16, v39
	v_and_b32_e32 v59, 0xffff0000, v39
	v_pk_add_f32 v[38:39], v[44:45], 1.0 op_sel_hi:[1,0] neg_lo:[1,0] neg_hi:[1,0]
	v_cndmask_b32_e64 v25, 0, 32, vcc
	v_cmp_gt_f32_e64 s[2:3], s11, v27
	v_pk_fma_f32 v[28:29], v[38:39], v[28:29], v[44:45]
	v_ldexp_f32 v25, v26, v25
	v_cndmask_b32_e64 v30, 0, 32, s[2:3]
	v_cmp_gt_f32_e64 s[4:5], s11, v28
	v_ldexp_f32 v30, v27, v30
	v_log_f32_e32 v25, v25
	v_cndmask_b32_e64 v31, 0, 32, s[4:5]
	v_log_f32_e32 v30, v30
	v_ldexp_f32 v31, v28, v31
	v_log_f32_e32 v31, v31
	v_lshlrev_b32_e32 v62, 16, v41
	v_and_b32_e32 v63, 0xffff0000, v41
	v_mul_f32_e32 v41, 0x3f317217, v25
	v_cmp_gt_f32_e64 s[6:7], s11, v29
	v_mul_f32_e32 v42, 0x3f317217, v30
	v_fma_f32 v41, v25, s16, -v41
	v_cndmask_b32_e64 v38, 0, 32, s[6:7]
	v_fma_f32 v42, v30, s16, -v42
	v_fmac_f32_e32 v41, 0x3377d1cf, v25
	v_cndmask_b32_e32 v39, 0, v46, vcc
	v_ldexp_f32 v38, v29, v38
	v_mul_f32_e32 v43, 0x3f317217, v31
	v_fmac_f32_e32 v42, 0x3377d1cf, v30
	v_fmac_f32_e32 v41, 0x3f317217, v25
	v_cmp_lt_f32_e64 vcc, |v25|, s17
	v_log_f32_e32 v38, v38
	v_fma_f32 v43, v31, s16, -v43
	v_fmac_f32_e32 v42, 0x3f317217, v30
	v_cndmask_b32_e32 v25, v25, v41, vcc
	v_cmp_lt_f32_e64 vcc, |v30|, s17
	v_lshlrev_b32_e32 v60, 16, v40
	v_and_b32_e32 v61, 0xffff0000, v40
	v_cndmask_b32_e64 v40, 0, v46, s[2:3]
	v_fmac_f32_e32 v43, 0x3377d1cf, v31
	v_cndmask_b32_e32 v30, v30, v42, vcc
	v_fmac_f32_e32 v43, 0x3f317217, v31
	v_sub_f32_e32 v25, v25, v39
	v_sub_f32_e32 v30, v30, v40
	v_cmp_lt_f32_e64 vcc, |v31|, s17
	ds_write2_b32 v47, v25, v30 offset1:1
	v_cndmask_b32_e64 v30, 0, v46, s[4:5]
	v_cndmask_b32_e32 v25, v31, v43, vcc
	v_sub_f32_e32 v25, v25, v30
	v_mul_f32_e32 v30, 0x3f317217, v38
	v_fma_f32 v39, v38, s16, -v30
	v_mul_f32_e32 v30, 0xbfb8aa3b, v52
	v_mul_f32_e32 v31, 0xbfb8aa3b, v53
	v_exp_f32_e32 v30, v30
	v_exp_f32_e32 v31, v31
	v_fmac_f32_e32 v39, 0x3377d1cf, v38
	v_fmac_f32_e32 v39, 0x3f317217, v38
	v_add_f32_e32 v30, 1.0, v30
	v_add_f32_e32 v31, 1.0, v31
	v_rcp_f32_e32 v30, v30
	v_rcp_f32_e32 v31, v31
	v_cmp_lt_f32_e64 vcc, |v38|, s17
	v_ashrrev_i32_e32 v52, 7, v36
	s_nop 0
	v_cndmask_b32_e32 v40, v38, v39, vcc
	s_nop 0
	v_pk_add_f32 v[38:39], v[48:49], 1.0 op_sel_hi:[1,0] neg_lo:[1,0] neg_hi:[1,0]
	s_nop 0
	v_pk_fma_f32 v[30:31], v[30:31], v[38:39], v[48:49]
	v_cndmask_b32_e64 v39, 0, v46, s[6:7]
	v_cmp_gt_f32_e32 vcc, s11, v30
	v_sub_f32_e32 v39, v40, v39
	v_cmp_gt_f32_e64 s[2:3], s11, v31
	v_cndmask_b32_e64 v38, 0, 32, vcc
	v_ldexp_f32 v38, v30, v38
	v_log_f32_e32 v38, v38
	ds_write2_b32 v47, v25, v39 offset0:2 offset1:3
	v_cndmask_b32_e64 v39, 0, 32, s[2:3]
	v_ldexp_f32 v39, v31, v39
	v_mul_f32_e32 v25, 0x3f317217, v38
	v_fma_f32 v25, v38, s16, -v25
	v_log_f32_e32 v40, v39
	v_fmac_f32_e32 v25, 0x3377d1cf, v38
	v_fmac_f32_e32 v25, 0x3f317217, v38
	v_cmp_lt_f32_e64 s[4:5], |v38|, s17
	v_mul_f32_e32 v39, 0xbfb8aa3b, v55
	v_exp_f32_e32 v39, v39
	v_cndmask_b32_e64 v25, v38, v25, s[4:5]
	v_cndmask_b32_e32 v38, 0, v46, vcc
	v_sub_f32_e32 v25, v25, v38
	v_mul_f32_e32 v38, 0x3f317217, v40
	v_fma_f32 v41, v40, s16, -v38
	v_mul_f32_e32 v38, 0xbfb8aa3b, v54
	v_exp_f32_e32 v38, v38
	v_add_f32_e32 v39, 1.0, v39
	v_rcp_f32_e32 v39, v39
	v_fmac_f32_e32 v41, 0x3377d1cf, v40
	v_add_f32_e32 v38, 1.0, v38
	v_rcp_f32_e32 v38, v38
	v_fmac_f32_e32 v41, 0x3f317217, v40
	v_cmp_lt_f32_e64 vcc, |v40|, s17
	s_nop 1
	v_cndmask_b32_e32 v42, v40, v41, vcc
	v_pk_add_f32 v[40:41], v[50:51], 1.0 op_sel_hi:[1,0] neg_lo:[1,0] neg_hi:[1,0]
	s_nop 0
	v_pk_fma_f32 v[38:39], v[38:39], v[40:41], v[50:51]
	v_cndmask_b32_e64 v41, 0, v46, s[2:3]
	v_cmp_gt_f32_e32 vcc, s11, v38
	v_sub_f32_e32 v41, v42, v41
	v_cmp_gt_f32_e64 s[2:3], s11, v39
	v_cndmask_b32_e64 v40, 0, 32, vcc
	v_ldexp_f32 v40, v38, v40
	v_log_f32_e32 v40, v40
	ds_write2_b32 v47, v25, v41 offset0:4 offset1:5
	v_cndmask_b32_e64 v41, 0, 32, s[2:3]
	v_ldexp_f32 v41, v39, v41
	v_mul_f32_e32 v25, 0x3f317217, v40
	v_fma_f32 v25, v40, s16, -v25
	v_log_f32_e32 v42, v41
	v_fmac_f32_e32 v25, 0x3377d1cf, v40
	v_fmac_f32_e32 v25, 0x3f317217, v40
	v_cmp_lt_f32_e64 s[4:5], |v40|, s17
	v_mul_f32_e32 v41, 0xbfb8aa3b, v57
	v_exp_f32_e32 v41, v41
	v_cndmask_b32_e64 v25, v40, v25, s[4:5]
	v_cndmask_b32_e32 v40, 0, v46, vcc
	v_sub_f32_e32 v25, v25, v40
	v_mul_f32_e32 v40, 0x3f317217, v42
	v_fma_f32 v43, v42, s16, -v40
	v_mul_f32_e32 v40, 0xbfb8aa3b, v56
	v_exp_f32_e32 v40, v40
	v_add_f32_e32 v41, 1.0, v41
	v_rcp_f32_e32 v41, v41
	v_fmac_f32_e32 v43, 0x3377d1cf, v42
	v_add_f32_e32 v40, 1.0, v40
	v_rcp_f32_e32 v40, v40
	v_fmac_f32_e32 v43, 0x3f317217, v42
	v_cmp_lt_f32_e64 vcc, |v42|, s17
	v_and_b32_e32 v51, 0x7f, v36
	s_nop 0
	v_cndmask_b32_e32 v44, v42, v43, vcc
	s_nop 0
	v_pk_add_f32 v[42:43], v[20:21], 1.0 op_sel_hi:[1,0] neg_lo:[1,0] neg_hi:[1,0]
	s_nop 0
	v_pk_fma_f32 v[20:21], v[40:41], v[42:43], v[20:21]
	v_cndmask_b32_e64 v41, 0, v46, s[2:3]
	v_cmp_gt_f32_e32 vcc, s11, v20
	v_sub_f32_e32 v41, v44, v41
	v_cmp_gt_f32_e64 s[2:3], s11, v21
	v_cndmask_b32_e64 v40, 0, 32, vcc
	v_ldexp_f32 v40, v20, v40
	v_log_f32_e32 v40, v40
	ds_write2_b32 v47, v25, v41 offset0:6 offset1:7
	v_cndmask_b32_e64 v41, 0, 32, s[2:3]
	v_ldexp_f32 v41, v21, v41
	v_mul_f32_e32 v25, 0x3f317217, v40
	v_fma_f32 v25, v40, s16, -v25
	v_log_f32_e32 v42, v41
	v_fmac_f32_e32 v25, 0x3377d1cf, v40
	v_fmac_f32_e32 v25, 0x3f317217, v40
	v_cmp_lt_f32_e64 s[4:5], |v40|, s17
	v_mul_f32_e32 v41, 0xbfb8aa3b, v59
	v_exp_f32_e32 v41, v41
	v_cndmask_b32_e64 v25, v40, v25, s[4:5]
	v_cndmask_b32_e32 v40, 0, v46, vcc
	v_sub_f32_e32 v25, v25, v40
	v_mul_f32_e32 v40, 0x3f317217, v42
	v_fma_f32 v43, v42, s16, -v40
	v_mul_f32_e32 v40, 0xbfb8aa3b, v58
	v_exp_f32_e32 v40, v40
	v_add_f32_e32 v41, 1.0, v41
	v_rcp_f32_e32 v41, v41
	v_fmac_f32_e32 v43, 0x3377d1cf, v42
	v_add_f32_e32 v40, 1.0, v40
	v_rcp_f32_e32 v40, v40
	v_fmac_f32_e32 v43, 0x3f317217, v42
	v_cmp_lt_f32_e64 vcc, |v42|, s17
	s_nop 1
	v_cndmask_b32_e32 v44, v42, v43, vcc
	v_pk_add_f32 v[42:43], v[22:23], 1.0 op_sel_hi:[1,0] neg_lo:[1,0] neg_hi:[1,0]
	s_nop 0
	v_pk_fma_f32 v[40:41], v[40:41], v[42:43], v[22:23]
	v_cndmask_b32_e64 v23, 0, v46, s[2:3]
	v_cmp_gt_f32_e32 vcc, s11, v40
	v_sub_f32_e32 v23, v44, v23
	v_cmp_gt_f32_e64 s[2:3], s11, v41
	v_cndmask_b32_e64 v22, 0, 32, vcc
	v_ldexp_f32 v22, v40, v22
	v_log_f32_e32 v22, v22
	ds_write2_b32 v47, v25, v23 offset0:8 offset1:9
	v_cndmask_b32_e64 v25, 0, 32, s[2:3]
	v_ldexp_f32 v25, v41, v25
	v_mul_f32_e32 v23, 0x3f317217, v22
	v_fma_f32 v23, v22, s16, -v23
	v_log_f32_e32 v25, v25
	v_fmac_f32_e32 v23, 0x3377d1cf, v22
	v_fmac_f32_e32 v23, 0x3f317217, v22
	v_cmp_lt_f32_e64 s[4:5], |v22|, s17
	s_nop 1
	v_cndmask_b32_e64 v22, v22, v23, s[4:5]
	v_cndmask_b32_e32 v23, 0, v46, vcc
	v_sub_f32_e32 v44, v22, v23
	v_mul_f32_e32 v22, 0x3f317217, v25
	v_fma_f32 v42, v25, s16, -v22
	v_mul_f32_e32 v22, 0xbfb8aa3b, v60
	v_mul_f32_e32 v23, 0xbfb8aa3b, v61
	v_exp_f32_e32 v22, v22
	v_exp_f32_e32 v23, v23
	v_fmac_f32_e32 v42, 0x3377d1cf, v25
	v_fmac_f32_e32 v42, 0x3f317217, v25
	v_add_f32_e32 v22, 1.0, v22
	v_add_f32_e32 v23, 1.0, v23
	v_rcp_f32_e32 v22, v22
	v_rcp_f32_e32 v23, v23
	v_cmp_lt_f32_e64 vcc, |v25|, s17
	s_nop 1
	v_cndmask_b32_e32 v25, v25, v42, vcc
	v_pk_add_f32 v[42:43], v[16:17], 1.0 op_sel_hi:[1,0] neg_lo:[1,0] neg_hi:[1,0]
	s_nop 0
	v_pk_fma_f32 v[16:17], v[22:23], v[42:43], v[16:17]
	v_cndmask_b32_e64 v23, 0, v46, s[2:3]
	v_cmp_gt_f32_e32 vcc, s11, v16
	v_cmp_gt_f32_e64 s[2:3], s11, v17
	v_sub_f32_e32 v23, v25, v23
	v_cndmask_b32_e64 v22, 0, 32, vcc
	v_ldexp_f32 v22, v16, v22
	v_log_f32_e32 v22, v22
	v_cndmask_b32_e64 v25, 0, 32, s[2:3]
	ds_write2_b32 v47, v44, v23 offset0:10 offset1:11
	v_ldexp_f32 v25, v17, v25
	v_mul_f32_e32 v23, 0x3f317217, v22
	v_fma_f32 v23, v22, s16, -v23
	v_log_f32_e32 v25, v25
	v_fmac_f32_e32 v23, 0x3377d1cf, v22
	v_fmac_f32_e32 v23, 0x3f317217, v22
	v_cmp_lt_f32_e64 s[4:5], |v22|, s17
	s_nop 1
	v_cndmask_b32_e64 v22, v22, v23, s[4:5]
	v_cndmask_b32_e32 v23, 0, v46, vcc
	v_sub_f32_e32 v44, v22, v23
	v_mul_f32_e32 v22, 0x3f317217, v25
	v_fma_f32 v42, v25, s16, -v22
	v_mul_f32_e32 v22, 0xbfb8aa3b, v62
	v_mul_f32_e32 v23, 0xbfb8aa3b, v63
	v_exp_f32_e32 v22, v22
	v_exp_f32_e32 v23, v23
	v_fmac_f32_e32 v42, 0x3377d1cf, v25
	v_fmac_f32_e32 v42, 0x3f317217, v25
	v_add_f32_e32 v22, 1.0, v22
	v_add_f32_e32 v23, 1.0, v23
	v_rcp_f32_e32 v22, v22
	v_rcp_f32_e32 v23, v23
	v_cmp_lt_f32_e64 vcc, |v25|, s17
	s_nop 1
	v_cndmask_b32_e32 v25, v25, v42, vcc
	v_pk_add_f32 v[42:43], v[18:19], 1.0 op_sel_hi:[1,0] neg_lo:[1,0] neg_hi:[1,0]
	s_nop 0
	v_pk_fma_f32 v[42:43], v[22:23], v[42:43], v[18:19]
	v_cndmask_b32_e64 v19, 0, v46, s[2:3]
	v_cmp_gt_f32_e32 vcc, s11, v42
	v_cmp_gt_f32_e64 s[2:3], s11, v43
	v_sub_f32_e32 v19, v25, v19
	v_cndmask_b32_e64 v18, 0, 32, vcc
	v_ldexp_f32 v18, v42, v18
	v_log_f32_e32 v18, v18
	v_cndmask_b32_e64 v22, 0, 32, s[2:3]
	ds_write2_b32 v47, v44, v19 offset0:12 offset1:13
	v_ldexp_f32 v22, v43, v22
	v_mul_f32_e32 v19, 0x3f317217, v18
	v_fma_f32 v19, v18, s16, -v19
	v_log_f32_e32 v22, v22
	v_fmac_f32_e32 v19, 0x3377d1cf, v18
	v_fmac_f32_e32 v19, 0x3f317217, v18
	v_cmp_lt_f32_e64 s[4:5], |v18|, s17
	s_nop 1
	v_cndmask_b32_e64 v18, v18, v19, s[4:5]
	v_cndmask_b32_e32 v19, 0, v46, vcc
	v_sub_f32_e32 v18, v18, v19
	v_mul_f32_e32 v19, 0x3f317217, v22
	v_fma_f32 v19, v22, s16, -v19
	v_fmac_f32_e32 v19, 0x3377d1cf, v22
	v_fmac_f32_e32 v19, 0x3f317217, v22
	v_cmp_lt_f32_e64 vcc, |v22|, s17
	s_nop 1
	v_cndmask_b32_e32 v19, v22, v19, vcc
	v_cndmask_b32_e64 v22, 0, v46, s[2:3]
	v_sub_f32_e32 v19, v19, v22
	ds_write2_b32 v47, v18, v19 offset0:14 offset1:15
	v_lshl_add_u32 v18, v51, 2, 0
	v_mul_lo_u32 v19, v52, s19
	v_add_u32_e32 v18, v18, v19
	s_nop 0
	s_waitcnt lgkmcnt(0)
	s_barrier
	ds_read2_b32 v[44:45], v18 offset1:129
	v_add_u32_e32 v22, 0x400, v18
	ds_read2_b32 v[48:49], v22 offset0:2 offset1:131
	v_add_u32_e32 v25, 0x800, v18
	v_cmp_lt_i32_e32 vcc, 0, v52
	s_waitcnt lgkmcnt(1)
	v_add_f32_e32 v19, 0, v44
	v_add_f32_e32 v23, v19, v45
	ds_read2_b32 v[44:45], v25 offset0:4 offset1:133
	ds_write2_b32 v18, v19, v23 offset1:129
	s_waitcnt lgkmcnt(2)
	v_add_f32_e32 v19, v23, v48
	v_add_u32_e32 v23, 0xc00, v18
	v_add_f32_e32 v50, v19, v49
	ds_read2_b32 v[48:49], v23 offset0:6 offset1:135
	ds_write2_b32 v22, v19, v50 offset0:2 offset1:131
	s_waitcnt lgkmcnt(3)
	v_add_f32_e32 v19, v50, v44
	v_add_f32_e32 v44, v19, v45
	ds_write2_b32 v25, v19, v44 offset0:4 offset1:133
	s_waitcnt lgkmcnt(2)
	v_add_f32_e32 v45, v44, v48
	v_add_u32_e32 v44, 0x1000, v18
	ds_read2_b32 v[54:55], v44 offset0:8 offset1:137
	v_add_u32_e32 v19, 0x1400, v18
	v_add_f32_e32 v50, v45, v49
	ds_read2_b32 v[48:49], v19 offset0:10 offset1:139
	ds_write2_b32 v23, v45, v50 offset0:6 offset1:135
	s_waitcnt lgkmcnt(2)
	v_add_f32_e32 v45, v50, v54
	v_add_f32_e32 v50, v45, v55
	ds_write2_b32 v44, v45, v50 offset0:8 offset1:137
	v_add_u32_e32 v45, 0x1800, v18
	s_waitcnt lgkmcnt(2)
	v_add_f32_e32 v48, v50, v48
	ds_read2_b32 v[54:55], v45 offset0:12 offset1:141
	v_add_f32_e32 v50, v48, v49
	v_add_u32_e32 v49, 0x1c00, v18
	ds_read2_b32 v[56:57], v49 offset0:14 offset1:143
	ds_write2_b32 v19, v48, v50 offset0:10 offset1:139
	s_waitcnt lgkmcnt(2)
	v_add_f32_e32 v48, v50, v54
	v_add_f32_e32 v50, v48, v55
	ds_write2_b32 v45, v48, v50 offset0:12 offset1:141
	s_waitcnt lgkmcnt(2)
	v_add_f32_e32 v48, v50, v56
	v_add_f32_e32 v50, v48, v57
	ds_write2_b32 v49, v48, v50 offset0:14 offset1:143
	v_lshl_add_u32 v48, v36, 2, 0
	ds_write_b32 v48, v50 offset:33024
	s_waitcnt lgkmcnt(0)
	s_barrier
	s_and_saveexec_b64 s[2:3], vcc
	s_cbranch_execz .LBB0_218
	v_cmp_lt_u32_e32 vcc, 7, v52
	v_mov_b32_e32 v50, 0
	v_mov_b32_e32 v53, 0
	s_and_saveexec_b64 s[4:5], vcc
	s_cbranch_execz .LBB0_213
	v_and_b32_e32 v53, 0x7ffffff8, v52
	v_lshl_add_u32 v52, v51, 2, s21
	s_mov_b32 s28, 0
	v_mov_b32_e32 v50, 0
	s_mov_b64 s[6:7], 0

.LBB0_394:
	s_cmp_gt_i32 s20, 0
	s_cselect_b64 s[2:3], -1, 0
	s_and_b64 s[2:3], s[94:95], s[2:3]
	s_andn2_b64 vcc, exec, s[2:3]
	s_mov_b32 s15, 0
	s_cbranch_vccnz .LBB0_417
	s_add_i32 s2, s64, 64
	s_and_b64 s[0:1], s[0:1], exec
	s_cselect_b32 s8, s2, s10
	s_addk_i32 s8, 0x700
	s_add_u32 s0, s90, 0x1e800000
	s_addc_u32 s1, s91, 0
	v_readlane_b32 s2, v246, 36
	s_add_u32 s34, s90, 0x1ea00000
	v_readlane_b32 s3, v246, 37
	s_addc_u32 s35, s91, 0
	s_movk_i32 s9, 0x2880
	v_mov_b64_e32 v[32:33], s[2:3]
	s_movk_i32 s10, 0x1000
	s_mov_b32 s11, 0x800000
	s_mov_b32 s16, 0x3f317217
	s_mov_b32 s17, 0x7f800000
	v_mov_b32_e32 v46, 0x41b17218
	s_movk_i32 s18, 0x7f
	s_movk_i32 s19, 0x2040
	s_add_i32 s21, 0, 0x8100
	s_movk_i32 s22, 0x480
	s_movk_i32 s23, 0x48
	v_mov_b32_e32 v35, 0
	s_movk_i32 s24, 0x90
	s_mov_b32 s25, 0
	s_mov_b32 s99, s64
	s_lshl_b32 s100, s99, 3
	s_lshl_b32 s101, s99, 6
	s_and_b32 s100, s100, 0xffffe000
	s_and_b32 s101, s101, 0x1fc0
	s_or_b32 s100, s100, s101
	s_and_b32 s98, s99, 0x380
	v_ashrrev_i32_e32 v206, 6, v210
	v_bfi_b32 v208, -4, v206, v210
	v_lshlrev_b32_e32 v208, 4, v208
	v_mov_b32_e32 v209, 0
	v_bfe_u32 v206, v210, 2, 6
	v_or_b32_e32 v206, s100, v206
	v_mad_i64_i32 v[200:201], vcc, v206, s9, v[32:33]
	s_lshl_b32 s100, s98, 1
	s_mov_b32 s101, 0
	v_lshl_add_u64 v[200:201], v[200:201], 0, s[100:101]
	v_lshl_add_u64 v[200:201], v[208:209], 1, v[200:201]
	v_add_u32_e32 v202, s98, v208
	v_mov_b32_e32 v203, 0
	v_lshl_add_u64 v[202:203], v[202:203], 2, s[54:55]
	s_movk_i32 s100, 0x1000
	v_lshl_add_u64 v[204:205], v[200:201], 0, s[100:101]
	global_load_dwordx4 v[160:163], v[200:201], off offset:2048
	global_load_dwordx4 v[164:167], v[200:201], off offset:2064
	global_load_dwordx4 v[168:171], v[202:203], off
	global_load_dwordx4 v[172:175], v[202:203], off offset:16
	global_load_dwordx4 v[176:179], v[200:201], off offset:16
	global_load_dwordx4 v[180:183], v[200:201], off
	global_load_dwordx4 v[184:187], v[204:205], off
	global_load_dwordx4 v[188:191], v[204:205], off offset:16
	global_load_dwordx4 v[192:195], v[202:203], off offset:48
	global_load_dwordx4 v[196:199], v[202:203], off offset:32
	s_branch .LBB0_397

.LBB0_403:
	s_lshl_b32 s2, s56, 3
	s_lshl_b32 s3, s56, 6
	v_mov_b32_e32 v36, v210
	s_and_b32 s2, s2, 0xffffe000
	s_and_b32 s3, s3, 0x1fc0
	s_or_b32 s27, s2, s3
	v_ashrrev_i32_e32 v0, 6, v36
	v_bfe_u32 v37, v36, 2, 6
	s_and_b32 s4, s56, 0x380
	v_bfi_b32 v34, -4, v0, v36
	v_or_b32_e32 v0, s27, v37
	v_lshlrev_b32_e32 v24, 4, v34
	v_mad_i64_i32 v[0:1], s[2:3], v0, s9, v[32:33]
	s_lshl_b32 s14, s4, 1
	v_lshl_add_u64 v[0:1], v[0:1], 0, s[14:15]
	v_ashrrev_i32_e32 v25, 31, v24
	v_lshl_add_u64 v[0:1], v[24:25], 1, v[0:1]
	s_waitcnt vmcnt(0)
	v_mov_b32_e32 v26, v160
	v_mov_b32_e32 v27, v161
	v_mov_b32_e32 v28, v162
	v_mov_b32_e32 v29, v163
	v_mov_b32_e32 v38, v164
	v_mov_b32_e32 v39, v165
	v_mov_b32_e32 v40, v166
	v_mov_b32_e32 v41, v167
	v_add_u32_e32 v2, s4, v24
	v_ashrrev_i32_e32 v3, 31, v2
	v_lshl_add_u64 v[20:21], v[2:3], 2, s[54:55]
	v_mov_b32_e32 v42, v168
	v_mov_b32_e32 v43, v169
	v_mov_b32_e32 v44, v170
	v_mov_b32_e32 v45, v171
	v_mov_b32_e32 v48, v172
	v_mov_b32_e32 v49, v173
	v_mov_b32_e32 v50, v174
	v_mov_b32_e32 v51, v175
	v_mul_u32_u24_e32 v2, 0x204, v37
	v_lshlrev_b32_e32 v3, 6, v34
	v_add3_u32 v47, 0, v2, v3
	v_add_co_u32_e32 v2, vcc, s10, v0
	v_readfirstlane_b32 s26, v36
	s_nop 0
	v_addc_co_u32_e32 v3, vcc, 0, v1, vcc
	v_mov_b32_e32 v4, v176
	v_mov_b32_e32 v5, v177
	v_mov_b32_e32 v6, v178
	v_mov_b32_e32 v7, v179
	v_mov_b32_e32 v12, v180
	v_mov_b32_e32 v13, v181
	v_mov_b32_e32 v14, v182
	v_mov_b32_e32 v15, v183
	v_mov_b32_e32 v8, v184
	v_mov_b32_e32 v9, v185
	v_mov_b32_e32 v10, v186
	v_mov_b32_e32 v11, v187
	s_nop 0
	v_mov_b32_e32 v0, v188
	v_mov_b32_e32 v1, v189
	v_mov_b32_e32 v2, v190
	v_mov_b32_e32 v3, v191
	s_nop 0
	v_mov_b32_e32 v16, v192
	v_mov_b32_e32 v17, v193
	v_mov_b32_e32 v18, v194
	v_mov_b32_e32 v19, v195
	s_nop 0
	v_mov_b32_e32 v20, v196
	v_mov_b32_e32 v21, v197
	v_mov_b32_e32 v22, v198
	v_mov_b32_e32 v23, v199
	s_add_i32 s98, s25, 1
	s_cmp_ge_u32 s98, s20
	s_cbranch_scc1 .Lpa2_nopf
	s_lshl_b32 s99, s98, 8
	s_add_i32 s99, s99, s64
	s_cmp_gt_u32 s98, 7
	s_cselect_b32 s99, s8, s99
	s_lshl_b32 s100, s99, 3
	s_lshl_b32 s101, s99, 6
	s_and_b32 s100, s100, 0xffffe000
	s_and_b32 s101, s101, 0x1fc0
	s_or_b32 s100, s100, s101
	s_and_b32 s98, s99, 0x380
	v_ashrrev_i32_e32 v206, 6, v210
	v_bfi_b32 v208, -4, v206, v210
	v_lshlrev_b32_e32 v208, 4, v208
	v_mov_b32_e32 v209, 0
	v_bfe_u32 v206, v210, 2, 6
	v_or_b32_e32 v206, s100, v206
	v_mad_i64_i32 v[200:201], vcc, v206, s9, v[32:33]
	s_lshl_b32 s100, s98, 1
	s_mov_b32 s101, 0
	v_lshl_add_u64 v[200:201], v[200:201], 0, s[100:101]
	v_lshl_add_u64 v[200:201], v[208:209], 1, v[200:201]
	v_add_u32_e32 v202, s98, v208
	v_mov_b32_e32 v203, 0
	v_lshl_add_u64 v[202:203], v[202:203], 2, s[54:55]
	s_movk_i32 s100, 0x1000
	v_lshl_add_u64 v[204:205], v[200:201], 0, s[100:101]
	global_load_dwordx4 v[160:163], v[200:201], off offset:2048
	global_load_dwordx4 v[164:167], v[200:201], off offset:2064
	global_load_dwordx4 v[168:171], v[202:203], off
	global_load_dwordx4 v[172:175], v[202:203], off offset:16
	global_load_dwordx4 v[176:179], v[200:201], off offset:16
	global_load_dwordx4 v[180:183], v[200:201], off
	global_load_dwordx4 v[184:187], v[204:205], off
	global_load_dwordx4 v[188:191], v[204:205], off offset:16
	global_load_dwordx4 v[192:195], v[202:203], off offset:48
	global_load_dwordx4 v[196:199], v[202:203], off offset:32
.Lpa2_nopf:
	s_nop 0
	v_lshlrev_b32_e32 v25, 16, v26
	v_and_b32_e32 v26, 0xffff0000, v26
	v_lshlrev_b32_e32 v30, 16, v27
	v_and_b32_e32 v27, 0xffff0000, v27
	v_mul_f32_e32 v25, 0xbfb8aa3b, v25
	v_mul_f32_e32 v26, 0xbfb8aa3b, v26
	v_mul_f32_e32 v27, 0xbfb8aa3b, v27
	v_exp_f32_e32 v25, v25
	v_exp_f32_e32 v26, v26
	v_exp_f32_e32 v27, v27
	v_lshlrev_b32_e32 v52, 16, v28
	v_and_b32_e32 v53, 0xffff0000, v28
	v_mul_f32_e32 v28, 0xbfb8aa3b, v30
	v_exp_f32_e32 v28, v28
	v_lshlrev_b32_e32 v54, 16, v29
	v_and_b32_e32 v55, 0xffff0000, v29
	v_add_f32_e32 v25, 1.0, v25
	v_add_f32_e32 v29, 1.0, v26
	v_add_f32_e32 v30, 1.0, v27
	v_rcp_f32_e32 v26, v25
	v_rcp_f32_e32 v27, v29
	v_add_f32_e32 v28, 1.0, v28
	v_rcp_f32_e32 v28, v28
	v_rcp_f32_e32 v29, v30
	v_pk_add_f32 v[30:31], v[42:43], 1.0 op_sel_hi:[1,0] neg_lo:[1,0] neg_hi:[1,0]
	v_lshlrev_b32_e32 v56, 16, v38
	v_pk_fma_f32 v[26:27], v[30:31], v[26:27], v[42:43]
	v_and_b32_e32 v57, 0xffff0000, v38
	v_cmp_gt_f32_e32 vcc, s11, v26
	v_lshlrev_b32_e32 v58, 16, v39
	v_and_b32_e32 v59, 0xffff0000, v39
	v_pk_add_f32 v[38:39], v[44:45], 1.0 op_sel_hi:[1,0] neg_lo:[1,0] neg_hi:[1,0]
	v_cndmask_b32_e64 v25, 0, 32, vcc
	v_cmp_gt_f32_e64 s[2:3], s11, v27
	v_pk_fma_f32 v[28:29], v[38:39], v[28:29], v[44:45]
	v_ldexp_f32 v25, v26, v25
	v_cndmask_b32_e64 v30, 0, 32, s[2:3]
	v_cmp_gt_f32_e64 s[4:5], s11, v28
	v_ldexp_f32 v30, v27, v30
	v_log_f32_e32 v25, v25
	v_cndmask_b32_e64 v31, 0, 32, s[4:5]
	v_log_f32_e32 v30, v30
	v_ldexp_f32 v31, v28, v31
	v_log_f32_e32 v31, v31
	v_lshlrev_b32_e32 v62, 16, v41
	v_and_b32_e32 v63, 0xffff0000, v41
	v_mul_f32_e32 v41, 0x3f317217, v25
	v_cmp_gt_f32_e64 s[6:7], s11, v29
	v_mul_f32_e32 v42, 0x3f317217, v30
	v_fma_f32 v41, v25, s16, -v41
	v_cndmask_b32_e64 v38, 0, 32, s[6:7]
	v_fma_f32 v42, v30, s16, -v42
	v_fmac_f32_e32 v41, 0x3377d1cf, v25
	v_cndmask_b32_e32 v39, 0, v46, vcc
	v_ldexp_f32 v38, v29, v38
	v_mul_f32_e32 v43, 0x3f317217, v31
	v_fmac_f32_e32 v42, 0x3377d1cf, v30
	v_fmac_f32_e32 v41, 0x3f317217, v25
	v_cmp_lt_f32_e64 vcc, |v25|, s17
	v_log_f32_e32 v38, v38
	v_fma_f32 v43, v31, s16, -v43
	v_fmac_f32_e32 v42, 0x3f317217, v30
	v_cndmask_b32_e32 v25, v25, v41, vcc
	v_cmp_lt_f32_e64 vcc, |v30|, s17
	v_lshlrev_b32_e32 v60, 16, v40
	v_and_b32_e32 v61, 0xffff0000, v40
	v_cndmask_b32_e64 v40, 0, v46, s[2:3]
	v_fmac_f32_e32 v43, 0x3377d1cf, v31
	v_cndmask_b32_e32 v30, v30, v42, vcc
	v_fmac_f32_e32 v43, 0x3f317217, v31
	v_sub_f32_e32 v25, v25, v39
	v_sub_f32_e32 v30, v30, v40
	v_cmp_lt_f32_e64 vcc, |v31|, s17
	ds_write2_b32 v47, v25, v30 offset1:1
	v_cndmask_b32_e64 v30, 0, v46, s[4:5]
	v_cndmask_b32_e32 v25, v31, v43, vcc
	v_sub_f32_e32 v25, v25, v30
	v_mul_f32_e32 v30, 0x3f317217, v38
	v_fma_f32 v39, v38, s16, -v30
	v_mul_f32_e32 v30, 0xbfb8aa3b, v52
	v_mul_f32_e32 v31, 0xbfb8aa3b, v53
	v_exp_f32_e32 v30, v30
	v_exp_f32_e32 v31, v31
	v_fmac_f32_e32 v39, 0x3377d1cf, v38
	v_fmac_f32_e32 v39, 0x3f317217, v38
	v_add_f32_e32 v30, 1.0, v30
	v_add_f32_e32 v31, 1.0, v31
	v_rcp_f32_e32 v30, v30
	v_rcp_f32_e32 v31, v31
	v_cmp_lt_f32_e64 vcc, |v38|, s17
	v_ashrrev_i32_e32 v52, 7, v36
	s_nop 0
	v_cndmask_b32_e32 v40, v38, v39, vcc
	v_pk_add_f32 v[38:39], v[48:49], 1.0 op_sel_hi:[1,0] neg_lo:[1,0] neg_hi:[1,0]
	s_nop 0
	v_pk_fma_f32 v[30:31], v[30:31], v[38:39], v[48:49]
	v_cndmask_b32_e64 v39, 0, v46, s[6:7]
	v_cmp_gt_f32_e32 vcc, s11, v30
	v_sub_f32_e32 v39, v40, v39
	v_cmp_gt_f32_e64 s[2:3], s11, v31
	v_cndmask_b32_e64 v38, 0, 32, vcc
	v_ldexp_f32 v38, v30, v38
	v_log_f32_e32 v38, v38
	ds_write2_b32 v47, v25, v39 offset0:2 offset1:3
	v_cndmask_b32_e64 v39, 0, 32, s[2:3]
	v_ldexp_f32 v39, v31, v39
	v_mul_f32_e32 v25, 0x3f317217, v38
	v_fma_f32 v25, v38, s16, -v25
	v_log_f32_e32 v40, v39
	v_fmac_f32_e32 v25, 0x3377d1cf, v38
	v_fmac_f32_e32 v25, 0x3f317217, v38
	v_cmp_lt_f32_e64 s[4:5], |v38|, s17
	v_mul_f32_e32 v39, 0xbfb8aa3b, v55
	v_exp_f32_e32 v39, v39
	v_cndmask_b32_e64 v25, v38, v25, s[4:5]
	v_cndmask_b32_e32 v38, 0, v46, vcc
	v_sub_f32_e32 v25, v25, v38
	v_mul_f32_e32 v38, 0x3f317217, v40
	v_fma_f32 v41, v40, s16, -v38
	v_mul_f32_e32 v38, 0xbfb8aa3b, v54
	v_exp_f32_e32 v38, v38
	v_add_f32_e32 v39, 1.0, v39
	v_rcp_f32_e32 v39, v39
	v_fmac_f32_e32 v41, 0x3377d1cf, v40
	v_add_f32_e32 v38, 1.0, v38
	v_rcp_f32_e32 v38, v38
	v_fmac_f32_e32 v41, 0x3f317217, v40
	v_cmp_lt_f32_e64 vcc, |v40|, s17
	s_nop 1
	v_cndmask_b32_e32 v42, v40, v41, vcc
	v_pk_add_f32 v[40:41], v[50:51], 1.0 op_sel_hi:[1,0] neg_lo:[1,0] neg_hi:[1,0]
	s_nop 0
	v_pk_fma_f32 v[38:39], v[38:39], v[40:41], v[50:51]
	v_cndmask_b32_e64 v41, 0, v46, s[2:3]
	v_cmp_gt_f32_e32 vcc, s11, v38
	v_sub_f32_e32 v41, v42, v41
	v_cmp_gt_f32_e64 s[2:3], s11, v39
	v_cndmask_b32_e64 v40, 0, 32, vcc
	v_ldexp_f32 v40, v38, v40
	v_log_f32_e32 v40, v40
	ds_write2_b32 v47, v25, v41 offset0:4 offset1:5
	v_cndmask_b32_e64 v41, 0, 32, s[2:3]
	v_ldexp_f32 v41, v39, v41
	v_mul_f32_e32 v25, 0x3f317217, v40
	v_fma_f32 v25, v40, s16, -v25
	v_log_f32_e32 v42, v41
	v_fmac_f32_e32 v25, 0x3377d1cf, v40
	v_fmac_f32_e32 v25, 0x3f317217, v40
	v_cmp_lt_f32_e64 s[4:5], |v40|, s17
	v_mul_f32_e32 v41, 0xbfb8aa3b, v57
	v_exp_f32_e32 v41, v41
	v_cndmask_b32_e64 v25, v40, v25, s[4:5]
	v_cndmask_b32_e32 v40, 0, v46, vcc
	v_sub_f32_e32 v25, v25, v40
	v_mul_f32_e32 v40, 0x3f317217, v42
	v_fma_f32 v43, v42, s16, -v40
	v_mul_f32_e32 v40, 0xbfb8aa3b, v56
	v_exp_f32_e32 v40, v40
	v_add_f32_e32 v41, 1.0, v41
	v_rcp_f32_e32 v41, v41
	v_fmac_f32_e32 v43, 0x3377d1cf, v42
	v_add_f32_e32 v40, 1.0, v40
	v_rcp_f32_e32 v40, v40
	v_fmac_f32_e32 v43, 0x3f317217, v42
	v_cmp_lt_f32_e64 vcc, |v42|, s17
	v_and_b32_e32 v51, 0x7f, v36
	s_nop 0
	v_cndmask_b32_e32 v44, v42, v43, vcc
	v_pk_add_f32 v[42:43], v[20:21], 1.0 op_sel_hi:[1,0] neg_lo:[1,0] neg_hi:[1,0]
	s_nop 0
	v_pk_fma_f32 v[20:21], v[40:41], v[42:43], v[20:21]
	v_cndmask_b32_e64 v41, 0, v46, s[2:3]
	v_cmp_gt_f32_e32 vcc, s11, v20
	v_sub_f32_e32 v41, v44, v41
	v_cmp_gt_f32_e64 s[2:3], s11, v21
	v_cndmask_b32_e64 v40, 0, 32, vcc
	v_ldexp_f32 v40, v20, v40
	v_log_f32_e32 v40, v40
	ds_write2_b32 v47, v25, v41 offset0:6 offset1:7
	v_cndmask_b32_e64 v41, 0, 32, s[2:3]
	v_ldexp_f32 v41, v21, v41
	v_mul_f32_e32 v25, 0x3f317217, v40
	v_fma_f32 v25, v40, s16, -v25
	v_log_f32_e32 v42, v41
	v_fmac_f32_e32 v25, 0x3377d1cf, v40
	v_fmac_f32_e32 v25, 0x3f317217, v40
	v_cmp_lt_f32_e64 s[4:5], |v40|, s17
	v_mul_f32_e32 v41, 0xbfb8aa3b, v59
	v_exp_f32_e32 v41, v41
	v_cndmask_b32_e64 v25, v40, v25, s[4:5]
	v_cndmask_b32_e32 v40, 0, v46, vcc
	v_sub_f32_e32 v25, v25, v40
	v_mul_f32_e32 v40, 0x3f317217, v42
	v_fma_f32 v43, v42, s16, -v40
	v_mul_f32_e32 v40, 0xbfb8aa3b, v58
	v_exp_f32_e32 v40, v40
	v_add_f32_e32 v41, 1.0, v41
	v_rcp_f32_e32 v41, v41
	v_fmac_f32_e32 v43, 0x3377d1cf, v42
	v_add_f32_e32 v40, 1.0, v40
	v_rcp_f32_e32 v40, v40
	v_fmac_f32_e32 v43, 0x3f317217, v42
	v_cmp_lt_f32_e64 vcc, |v42|, s17
	s_nop 1
	v_cndmask_b32_e32 v44, v42, v43, vcc
	v_pk_add_f32 v[42:43], v[22:23], 1.0 op_sel_hi:[1,0] neg_lo:[1,0] neg_hi:[1,0]
	s_nop 0
	v_pk_fma_f32 v[40:41], v[40:41], v[42:43], v[22:23]
	v_cndmask_b32_e64 v23, 0, v46, s[2:3]
	v_cmp_gt_f32_e32 vcc, s11, v40
	v_sub_f32_e32 v23, v44, v23
	v_cmp_gt_f32_e64 s[2:3], s11, v41
	v_cndmask_b32_e64 v22, 0, 32, vcc
	v_ldexp_f32 v22, v40, v22
	v_log_f32_e32 v22, v22
	ds_write2_b32 v47, v25, v23 offset0:8 offset1:9
	v_cndmask_b32_e64 v25, 0, 32, s[2:3]
	v_ldexp_f32 v25, v41, v25
	v_mul_f32_e32 v23, 0x3f317217, v22
	v_fma_f32 v23, v22, s16, -v23
	v_log_f32_e32 v25, v25
	v_fmac_f32_e32 v23, 0x3377d1cf, v22
	v_fmac_f32_e32 v23, 0x3f317217, v22
	v_cmp_lt_f32_e64 s[4:5], |v22|, s17
	s_nop 1
	v_cndmask_b32_e64 v22, v22, v23, s[4:5]
	v_cndmask_b32_e32 v23, 0, v46, vcc
	v_sub_f32_e32 v44, v22, v23
	v_mul_f32_e32 v22, 0x3f317217, v25
	v_fma_f32 v42, v25, s16, -v22
	v_mul_f32_e32 v22, 0xbfb8aa3b, v60
	v_mul_f32_e32 v23, 0xbfb8aa3b, v61
	v_exp_f32_e32 v22, v22
	v_exp_f32_e32 v23, v23
	v_fmac_f32_e32 v42, 0x3377d1cf, v25
	v_fmac_f32_e32 v42, 0x3f317217, v25
	v_add_f32_e32 v22, 1.0, v22
	v_add_f32_e32 v23, 1.0, v23
	v_rcp_f32_e32 v22, v22
	v_rcp_f32_e32 v23, v23
	v_cmp_lt_f32_e64 vcc, |v25|, s17
	s_nop 1
	v_cndmask_b32_e32 v25, v25, v42, vcc
	v_pk_add_f32 v[42:43], v[16:17], 1.0 op_sel_hi:[1,0] neg_lo:[1,0] neg_hi:[1,0]
	s_nop 0
	v_pk_fma_f32 v[16:17], v[22:23], v[42:43], v[16:17]
	v_cndmask_b32_e64 v23, 0, v46, s[2:3]
	v_cmp_gt_f32_e32 vcc, s11, v16
	v_cmp_gt_f32_e64 s[2:3], s11, v17
	v_sub_f32_e32 v23, v25, v23
	v_cndmask_b32_e64 v22, 0, 32, vcc
	v_ldexp_f32 v22, v16, v22
	v_log_f32_e32 v22, v22
	v_cndmask_b32_e64 v25, 0, 32, s[2:3]
	ds_write2_b32 v47, v44, v23 offset0:10 offset1:11
	v_ldexp_f32 v25, v17, v25
	v_mul_f32_e32 v23, 0x3f317217, v22
	v_fma_f32 v23, v22, s16, -v23
	v_log_f32_e32 v25, v25
	v_fmac_f32_e32 v23, 0x3377d1cf, v22
	v_fmac_f32_e32 v23, 0x3f317217, v22
	v_cmp_lt_f32_e64 s[4:5], |v22|, s17
	s_nop 1
	v_cndmask_b32_e64 v22, v22, v23, s[4:5]
	v_cndmask_b32_e32 v23, 0, v46, vcc
	v_sub_f32_e32 v44, v22, v23
	v_mul_f32_e32 v22, 0x3f317217, v25
	v_fma_f32 v42, v25, s16, -v22
	v_mul_f32_e32 v22, 0xbfb8aa3b, v62
	v_mul_f32_e32 v23, 0xbfb8aa3b, v63
	v_exp_f32_e32 v22, v22
	v_exp_f32_e32 v23, v23
	v_fmac_f32_e32 v42, 0x3377d1cf, v25
	v_fmac_f32_e32 v42, 0x3f317217, v25
	v_add_f32_e32 v22, 1.0, v22
	v_add_f32_e32 v23, 1.0, v23
	v_rcp_f32_e32 v22, v22
	v_rcp_f32_e32 v23, v23
	v_cmp_lt_f32_e64 vcc, |v25|, s17
	s_nop 1
	v_cndmask_b32_e32 v25, v25, v42, vcc
	v_pk_add_f32 v[42:43], v[18:19], 1.0 op_sel_hi:[1,0] neg_lo:[1,0] neg_hi:[1,0]
	s_nop 0
	v_pk_fma_f32 v[42:43], v[22:23], v[42:43], v[18:19]
	v_cndmask_b32_e64 v19, 0, v46, s[2:3]
	v_cmp_gt_f32_e32 vcc, s11, v42
	v_cmp_gt_f32_e64 s[2:3], s11, v43
	v_sub_f32_e32 v19, v25, v19
	v_cndmask_b32_e64 v18, 0, 32, vcc
	v_ldexp_f32 v18, v42, v18
	v_log_f32_e32 v18, v18
	v_cndmask_b32_e64 v22, 0, 32, s[2:3]
	ds_write2_b32 v47, v44, v19 offset0:12 offset1:13
	v_ldexp_f32 v22, v43, v22
	v_mul_f32_e32 v19, 0x3f317217, v18
	v_fma_f32 v19, v18, s16, -v19
	v_log_f32_e32 v22, v22
	v_fmac_f32_e32 v19, 0x3377d1cf, v18
	v_fmac_f32_e32 v19, 0x3f317217, v18
	v_cmp_lt_f32_e64 s[4:5], |v18|, s17
	s_nop 1
	v_cndmask_b32_e64 v18, v18, v19, s[4:5]
	v_cndmask_b32_e32 v19, 0, v46, vcc
	v_sub_f32_e32 v18, v18, v19
	v_mul_f32_e32 v19, 0x3f317217, v22
	v_fma_f32 v19, v22, s16, -v19
	v_fmac_f32_e32 v19, 0x3377d1cf, v22
	v_fmac_f32_e32 v19, 0x3f317217, v22
	v_cmp_lt_f32_e64 vcc, |v22|, s17
	s_nop 1
	v_cndmask_b32_e32 v19, v22, v19, vcc
	v_cndmask_b32_e64 v22, 0, v46, s[2:3]
	v_sub_f32_e32 v19, v19, v22
	ds_write2_b32 v47, v18, v19 offset0:14 offset1:15
	v_lshl_add_u32 v18, v51, 2, 0
	v_mul_lo_u32 v19, v52, s19
	v_add_u32_e32 v18, v18, v19
	s_nop 0
	s_waitcnt lgkmcnt(0)
	s_barrier
	ds_read2_b32 v[44:45], v18 offset1:129
	v_add_u32_e32 v22, 0x400, v18
	ds_read2_b32 v[48:49], v22 offset0:2 offset1:131
	v_add_u32_e32 v25, 0x800, v18
	v_cmp_lt_i32_e32 vcc, 0, v52
	s_waitcnt lgkmcnt(1)
	v_add_f32_e32 v19, 0, v44
	v_add_f32_e32 v23, v19, v45
	ds_read2_b32 v[44:45], v25 offset0:4 offset1:133
	ds_write2_b32 v18, v19, v23 offset1:129
	s_waitcnt lgkmcnt(2)
	v_add_f32_e32 v19, v23, v48
	v_add_u32_e32 v23, 0xc00, v18
	v_add_f32_e32 v50, v19, v49
	ds_read2_b32 v[48:49], v23 offset0:6 offset1:135
	ds_write2_b32 v22, v19, v50 offset0:2 offset1:131
	s_waitcnt lgkmcnt(3)
	v_add_f32_e32 v19, v50, v44
	v_add_f32_e32 v44, v19, v45
	ds_write2_b32 v25, v19, v44 offset0:4 offset1:133
	s_waitcnt lgkmcnt(2)
	v_add_f32_e32 v45, v44, v48
	v_add_u32_e32 v44, 0x1000, v18
	ds_read2_b32 v[54:55], v44 offset0:8 offset1:137
	v_add_u32_e32 v19, 0x1400, v18
	v_add_f32_e32 v50, v45, v49
	ds_read2_b32 v[48:49], v19 offset0:10 offset1:139
	ds_write2_b32 v23, v45, v50 offset0:6 offset1:135
	s_waitcnt lgkmcnt(2)
	v_add_f32_e32 v45, v50, v54
	v_add_f32_e32 v50, v45, v55
	ds_write2_b32 v44, v45, v50 offset0:8 offset1:137
	v_add_u32_e32 v45, 0x1800, v18
	s_waitcnt lgkmcnt(2)
	v_add_f32_e32 v48, v50, v48
	ds_read2_b32 v[54:55], v45 offset0:12 offset1:141
	v_add_f32_e32 v50, v48, v49
	v_add_u32_e32 v49, 0x1c00, v18
	ds_read2_b32 v[56:57], v49 offset0:14 offset1:143
	ds_write2_b32 v19, v48, v50 offset0:10 offset1:139
	s_waitcnt lgkmcnt(2)
	v_add_f32_e32 v48, v50, v54
	v_add_f32_e32 v50, v48, v55
	ds_write2_b32 v45, v48, v50 offset0:12 offset1:141
	s_waitcnt lgkmcnt(2)
	v_add_f32_e32 v48, v50, v56
	v_add_f32_e32 v50, v48, v57
	ds_write2_b32 v49, v48, v50 offset0:14 offset1:143
	v_lshl_add_u32 v48, v36, 2, 0
	ds_write_b32 v48, v50 offset:33024
	s_waitcnt lgkmcnt(0)
	s_barrier
	s_and_saveexec_b64 s[2:3], vcc
	s_cbranch_execz .LBB0_413
	v_cmp_lt_u32_e32 vcc, 7, v52
	v_mov_b32_e32 v50, 0
	v_mov_b32_e32 v53, 0
	s_and_saveexec_b64 s[4:5], vcc
	s_cbranch_execz .LBB0_408
	v_and_b32_e32 v53, 0x7ffffff8, v52
	v_lshl_add_u32 v52, v51, 2, s21
	s_mov_b32 s28, 0
	v_mov_b32_e32 v50, 0
	s_mov_b64 s[6:7], 0
